# hot loop heads (GEMM K-loops, MLA, diff) aligned to 64 bytes with s_nop fill
# speedup vs baseline: 1.0067x; 1.0067x over previous
.LBB0_210:
	s_mul_hi_i32 s8, s10, 0x3e0f83e1
	s_lshr_b32 s9, s8, 31
	s_ashr_i32 s92, s8, 3
	s_add_i32 s92, s92, s9
	s_lshl_b32 s93, s10, 8
	s_mul_i32 s8, s92, 0xffffdf00
	s_add_i32 s40, s8, s93
	s_andn2_b64 vcc, exec, s[0:1]
	s_mov_b64 s[0:1], -1
	s_cbranch_vccnz .LBB0_246
	v_mov_b32_e32 v20, v190
	s_and_b32 s95, s94, 7
	s_lshl_b32 s10, s95, 8
	v_ashrrev_i32_e32 v16, 3, v20
	v_lshrrev_b32_e32 v21, 4, v20
	v_add_u32_e32 v23, s93, v16
	v_xor_b32_e32 v22, v21, v20
	v_add_u32_e32 v6, 64, v23
	v_mov_b64_e32 v[4:5], s[18:19]
	v_add_u32_e32 v10, 0x80, v23
	v_add_u32_e32 v14, 0xc0, v23
	v_add_u32_e32 v24, s10, v16
	v_mov_b64_e32 v[18:19], s[20:21]
	v_mad_i64_i32 v[0:1], s[0:1], v23, s78, 0
	v_mad_i64_i32 v[2:3], s[0:1], v6, s78, 0
	v_mad_i64_i32 v[6:7], s[0:1], v6, s78, v[4:5]
	v_mad_i64_i32 v[8:9], s[0:1], v10, s78, 0
	v_mad_i64_i32 v[10:11], s[0:1], v10, s78, v[4:5]
	v_mad_i64_i32 v[12:13], s[0:1], v14, s78, 0
	v_mad_i64_i32 v[14:15], s[0:1], v14, s78, v[4:5]
	v_mad_i64_i32 v[16:17], s[0:1], v24, s78, 0
	v_mad_i64_i32 v[18:19], s[0:1], v24, s78, v[18:19]
	v_mad_i64_i32 v[4:5], s[0:1], v23, s78, v[4:5]
	v_lshlrev_b32_e32 v22, 4, v22
	v_lshl_add_u32 v152, v20, 4, 0
	v_and_b32_e32 v176, 0x70, v22
	v_readfirstlane_b32 s0, v152
	v_lshl_add_u64 v[4:5], v[4:5], 0, v[176:177]
	s_mov_b32 m0, s0
	v_lshl_add_u64 v[6:7], v[6:7], 0, v[176:177]
	global_load_lds_dwordx4 v[4:5], off
	v_add_u32_e32 v4, 0x2000, v152
	v_lshl_add_u64 v[10:11], v[10:11], 0, v[176:177]
	v_readfirstlane_b32 s0, v4
	v_add_u32_e32 v4, 0x4000, v152
	s_mov_b32 m0, s0
	v_readfirstlane_b32 s0, v4
	v_add_u32_e32 v4, 0x6000, v152
	global_load_lds_dwordx4 v[6:7], off
	s_mov_b32 m0, s0
	v_readfirstlane_b32 s0, v4
	v_add_u32_e32 v4, 0x8000, v152
	v_lshl_add_u64 v[14:15], v[14:15], 0, v[176:177]
	global_load_lds_dwordx4 v[10:11], off
	s_mov_b32 m0, s0
	v_readfirstlane_b32 s0, v4
	v_lshl_add_u64 v[18:19], v[18:19], 0, v[176:177]
	global_load_lds_dwordx4 v[14:15], off
	s_mov_b32 m0, s0
	s_mov_b64 s[0:1], 0x22000
	v_add_u32_e32 v6, 0xa000, v152
	v_lshl_add_u64 v[4:5], v[18:19], 0, s[0:1]
	v_readfirstlane_b32 s0, v6
	global_load_lds_dwordx4 v[18:19], off
	s_mov_b32 m0, s0
	s_mov_b64 s[0:1], 0x44000
	v_add_u32_e32 v6, 0xc000, v152
	global_load_lds_dwordx4 v[4:5], off
	v_lshl_add_u64 v[4:5], v[18:19], 0, s[0:1]
	v_readfirstlane_b32 s0, v6
	s_mov_b32 m0, s0
	s_mov_b64 s[0:1], 0x66000
	v_add_u32_e32 v6, 0xe000, v152
	global_load_lds_dwordx4 v[4:5], off
	v_lshl_add_u64 v[4:5], v[18:19], 0, s[0:1]
	v_readfirstlane_b32 s0, v6
	s_mov_b32 m0, s0
	v_and_b32_e32 v147, 15, v20
	global_load_lds_dwordx4 v[4:5], off
	v_bfe_u32 v148, v20, 4, 2
	v_bfe_u32 v22, v20, 1, 3
	v_lshlrev_b32_e32 v23, 7, v147
	v_bitop3_b32 v24, v21, v22, 3 bitop3:0x6c
	v_bitop3_b32 v22, v148, v22, 4 bitop3:0x36
	v_bitop3_b32 v4, v21, 7, v20 bitop3:0x48
	v_lshl_or_b32 v150, v22, 4, v23
	v_ashrrev_i32_e32 v22, 1, v20
	v_lshlrev_b32_e32 v4, 4, v4
	v_bfe_u32 v146, v20, 7, 1
	v_and_b32_e32 v149, 0xffffff80, v22
	v_and_or_b32 v149, v20, 64, v149
	v_or_b32_e32 v16, v16, v4
	v_or_b32_e32 v12, v12, v4
	v_or_b32_e32 v8, v8, v4
	v_or_b32_e32 v2, v2, v4
	v_or_b32_e32 v0, v0, v4
	v_mov_b32_e32 v108, 0
	v_lshl_or_b32 v151, v24, 4, v23
	v_lshl_add_u64 v[128:129], s[62:63], 0, v[16:17]
	v_lshl_add_u64 v[130:131], s[64:65], 0, v[12:13]
	v_lshl_add_u64 v[132:133], s[64:65], 0, v[8:9]
	v_lshl_add_u64 v[134:135], s[64:65], 0, v[2:3]
	v_lshl_add_u64 v[144:145], s[64:65], 0, v[0:1]
	s_mov_b32 s0, 0
	s_mov_b64 s[8:9], 0
	v_mov_b32_e32 v109, v108
	v_mov_b32_e32 v110, v108
	v_mov_b32_e32 v111, v108
	v_mov_b32_e32 v0, v108
	v_mov_b32_e32 v1, v108
	v_mov_b32_e32 v2, v108
	v_mov_b32_e32 v3, v108
	v_mov_b32_e32 v4, v108
	v_mov_b32_e32 v5, v108
	v_mov_b32_e32 v6, v108
	v_mov_b32_e32 v7, v108
	v_mov_b32_e32 v8, v108
	v_mov_b32_e32 v9, v108
	v_mov_b32_e32 v10, v108
	v_mov_b32_e32 v11, v108
	v_mov_b32_e32 v16, v108
	v_mov_b32_e32 v17, v108
	v_mov_b32_e32 v18, v108
	v_mov_b32_e32 v19, v108
	v_mov_b32_e32 v24, v108
	v_mov_b32_e32 v25, v108
	v_mov_b32_e32 v26, v108
	v_mov_b32_e32 v27, v108
	v_mov_b32_e32 v32, v108
	v_mov_b32_e32 v33, v108
	v_mov_b32_e32 v34, v108
	v_mov_b32_e32 v35, v108
	v_mov_b32_e32 v40, v108
	v_mov_b32_e32 v41, v108
	v_mov_b32_e32 v42, v108
	v_mov_b32_e32 v43, v108
	v_mov_b32_e32 v12, v108
	v_mov_b32_e32 v13, v108
	v_mov_b32_e32 v14, v108
	v_mov_b32_e32 v15, v108
	v_mov_b32_e32 v20, v108
	v_mov_b32_e32 v21, v108
	v_mov_b32_e32 v22, v108
	v_mov_b32_e32 v23, v108
	v_mov_b32_e32 v28, v108
	v_mov_b32_e32 v29, v108
	v_mov_b32_e32 v30, v108
	v_mov_b32_e32 v31, v108
	v_mov_b32_e32 v36, v108
	v_mov_b32_e32 v37, v108
	v_mov_b32_e32 v38, v108
	v_mov_b32_e32 v39, v108
	v_mov_b32_e32 v48, v108
	v_mov_b32_e32 v49, v108
	v_mov_b32_e32 v50, v108
	v_mov_b32_e32 v51, v108
	v_mov_b32_e32 v56, v108
	v_mov_b32_e32 v57, v108
	v_mov_b32_e32 v58, v108
	v_mov_b32_e32 v59, v108
	v_mov_b32_e32 v64, v108
	v_mov_b32_e32 v65, v108
	v_mov_b32_e32 v66, v108
	v_mov_b32_e32 v67, v108
	v_mov_b32_e32 v72, v108
	v_mov_b32_e32 v73, v108
	v_mov_b32_e32 v74, v108
	v_mov_b32_e32 v75, v108
	v_mov_b32_e32 v44, v108
	v_mov_b32_e32 v45, v108
	v_mov_b32_e32 v46, v108
	v_mov_b32_e32 v47, v108
	v_mov_b32_e32 v52, v108
	v_mov_b32_e32 v53, v108
	v_mov_b32_e32 v54, v108
	v_mov_b32_e32 v55, v108
	v_mov_b32_e32 v60, v108
	v_mov_b32_e32 v61, v108
	v_mov_b32_e32 v62, v108
	v_mov_b32_e32 v63, v108
	v_mov_b32_e32 v68, v108
	v_mov_b32_e32 v69, v108
	v_mov_b32_e32 v70, v108
	v_mov_b32_e32 v71, v108
	v_mov_b32_e32 v80, v108
	v_mov_b32_e32 v81, v108
	v_mov_b32_e32 v82, v108
	v_mov_b32_e32 v83, v108
	v_mov_b32_e32 v88, v108
	v_mov_b32_e32 v89, v108
	v_mov_b32_e32 v90, v108
	v_mov_b32_e32 v91, v108
	v_mov_b32_e32 v96, v108
	v_mov_b32_e32 v97, v108
	v_mov_b32_e32 v98, v108
	v_mov_b32_e32 v99, v108
	v_mov_b32_e32 v104, v108
	v_mov_b32_e32 v105, v108
	v_mov_b32_e32 v106, v108
	v_mov_b32_e32 v107, v108
	v_mov_b32_e32 v76, v108
	v_mov_b32_e32 v77, v108
	v_mov_b32_e32 v78, v108
	v_mov_b32_e32 v79, v108
	v_mov_b32_e32 v84, v108
	v_mov_b32_e32 v85, v108
	v_mov_b32_e32 v86, v108
	v_mov_b32_e32 v87, v108
	v_mov_b32_e32 v92, v108
	v_mov_b32_e32 v93, v108
	v_mov_b32_e32 v94, v108
	v_mov_b32_e32 v95, v108
	v_mov_b32_e32 v100, v108
	v_mov_b32_e32 v101, v108
	v_mov_b32_e32 v102, v108
	v_mov_b32_e32 v103, v108
	v_mov_b32_e32 v112, v108
	v_mov_b32_e32 v113, v108
	v_mov_b32_e32 v114, v108
	v_mov_b32_e32 v115, v108
	v_mov_b32_e32 v116, v108
	v_mov_b32_e32 v117, v108
	v_mov_b32_e32 v118, v108
	v_mov_b32_e32 v119, v108
	v_mov_b32_e32 v120, v108
	v_mov_b32_e32 v121, v108
	v_mov_b32_e32 v122, v108
	v_mov_b32_e32 v123, v108
	v_mov_b32_e32 v124, v108
	v_mov_b32_e32 v125, v108
	v_mov_b32_e32 v126, v108
	v_mov_b32_e32 v127, v108
	v_lshlrev_b32_e32 v153, 7, v149
	v_lshlrev_b32_e32 v154, 14, v146
	.p2alignl 6, 3212836864

.LBB0_557:
	s_waitcnt vmcnt(0)
	s_mov_b64 s[0:1], 0
	.p2alignl 6, 3212836864

.LBB0_575:
	s_and_b32 s0, s11, -8
	s_cmpk_eq_i32 s0, 0x100
	s_cbranch_scc1 .LBB0_574
	s_lshl_b32 s1, s11, 5
	s_and_b32 s1, s1, 0xffffff00
	s_bfe_u32 s0, s11, 0x10002
	s_addk_i32 s1, 0x100
	s_cmpk_lt_i32 s11, 0x100
	s_mul_i32 s2, s0, 0x2100
	s_cselect_b32 s1, s1, 0
	v_mov_b32_e32 v6, v190
	s_cselect_b32 s17, 33, 1
	s_add_i32 s1, s1, s2
	s_load_dwordx2 s[8:9], s[4:5], 0xf0
	s_lshl_b32 s3, s11, 6
	v_and_b32_e32 v7, 31, v6
	v_ashrrev_i32_e32 v0, 1, v6
	v_and_b32_e32 v0, 0xffffffe0, v0
	v_or_b32_e32 v1, s1, v7
	v_add_u32_e32 v178, v1, v0
	v_ashrrev_i32_e32 v179, 31, v178
	s_and_b32 s16, s3, 0xc0
	v_lshlrev_b64 v[0:1], 9, v[178:179]
	v_bfe_u32 v206, v6, 5, 1
	s_waitcnt lgkmcnt(0)
	v_lshl_add_u64 v[0:1], s[8:9], 0, v[0:1]
	s_lshl_b32 s54, s16, 1
	s_lshl_b32 s0, s0, 8
	v_lshl_add_u64 v[0:1], v[0:1], 0, s[54:55]
	v_lshlrev_b32_e32 v176, 4, v206
	s_or_b32 s3, s0, s16
	v_lshl_add_u64 v[0:1], v[0:1], 0, v[176:177]
	s_mov_b64 s[0:1], 0x6d6a000
	v_lshl_add_u64 v[2:3], v[0:1], 0, s[0:1]
	s_mov_b32 s0, 0x6d6a000
	v_add_co_u32_e32 v0, vcc, s0, v0
	s_mulk_i32 s3, 0x4200
	s_nop 0
	v_addc_co_u32_e32 v1, vcc, 0, v1, vcc
	global_load_dwordx4 v[144:147], v[2:3], off offset:32
	global_load_dwordx4 v[148:151], v[2:3], off offset:64
	global_load_dwordx4 v[152:155], v[0:1], off
	global_load_dwordx4 v[156:159], v[2:3], off offset:96
	v_ashrrev_i32_e32 v0, 3, v6
	v_lshrrev_b32_e32 v1, 4, v6
	v_add_u32_e32 v0, s2, v0
	v_xor_b32_e32 v2, v1, v6
	v_ashrrev_i32_e32 v1, 31, v0
	s_add_u32 s0, s8, s3
	v_lshlrev_b64 v[0:1], 9, v[0:1]
	s_addc_u32 s1, s9, 0
	v_lshl_add_u64 v[0:1], s[8:9], 0, v[0:1]
	v_lshlrev_b32_e32 v2, 4, v2
	s_add_u32 s0, s0, 0x7dea000
	v_lshl_add_u64 v[0:1], v[0:1], 0, s[54:55]
	v_and_b32_e32 v2, 0x70, v2
	v_mov_b32_e32 v3, v177
	v_ashrrev_i32_e32 v4, 5, v6
	s_addc_u32 s1, s1, 0
	v_lshl_add_u64 v[0:1], v[0:1], 0, v[2:3]
	v_and_b32_e32 v2, 16, v6
	v_xor_b32_e32 v3, v4, v6
	v_and_or_b32 v5, v3, 15, v2
	v_mov_b64_e32 v[2:3], s[0:1]
	s_movk_i32 s0, 0x4200
	v_mad_i64_i32 v[2:3], s[0:1], v4, s0, v[2:3]
	v_lshlrev_b32_e32 v4, 4, v5
	v_mov_b32_e32 v5, v177
	v_lshrrev_b32_e32 v8, 5, v6
	v_lshl_add_u64 v[182:183], v[2:3], 0, v[4:5]
	v_lshrrev_b32_e32 v3, 1, v6
	v_lshlrev_b32_e32 v2, 1, v6
	v_and_b32_e32 v5, 4, v3
	v_xor_b32_e32 v3, v3, v8
	v_and_b32_e32 v4, 19, v6
	v_and_or_b32 v2, v2, 8, v5
	v_lshlrev_b32_e32 v3, 4, v3
	v_or_b32_e32 v5, v2, v4
	v_and_b32_e32 v9, 16, v3
	v_lshlrev_b32_e32 v3, 7, v5
	v_lshl_or_b32 v2, v2, 3, v9
	v_or_b32_e32 v5, v3, v2
	v_bitop3_b32 v10, v3, s81, v2 bitop3:0x36
	v_xor_b32_e32 v3, v8, v6
	v_lshlrev_b32_e32 v2, 9, v7
	v_lshlrev_b32_e32 v3, 4, v3
	v_and_or_b32 v179, v3, 16, v2
	v_lshlrev_b32_e32 v2, 4, v6
	v_add_u32_e32 v208, 0, v2
	s_mov_b64 s[2:3], 0x75aa000
	v_readfirstlane_b32 s0, v208
	s_mov_b32 m0, s0
	s_mov_b64 s[0:1], 0x75b2000
	v_add_u32_e32 v7, 0x2000, v208
	v_lshl_add_u64 v[180:181], v[0:1], 0, s[2:3]
	v_and_b32_e32 v207, 0xe0, v2
	v_lshl_add_u64 v[2:3], v[0:1], 0, s[0:1]
	v_readfirstlane_b32 s0, v7
	global_load_lds_dwordx4 v[180:181], off
	s_mov_b32 m0, s0
	s_mov_b64 s[0:1], 0x75ba000
	v_add_u32_e32 v7, 0x4000, v208
	global_load_lds_dwordx4 v[2:3], off
	v_lshl_add_u64 v[2:3], v[0:1], 0, s[0:1]
	v_readfirstlane_b32 s0, v7
	s_mov_b32 m0, s0
	s_mov_b64 s[0:1], 0x75c2000
	global_load_lds_dwordx4 v[2:3], off
	v_add_u32_e32 v2, 0x6000, v208
	v_lshl_add_u64 v[0:1], v[0:1], 0, s[0:1]
	v_readfirstlane_b32 s0, v2
	s_mov_b32 m0, s0
	v_lshlrev_b32_e32 v2, 7, v4
	global_load_lds_dwordx4 v[0:1], off
	v_add_u32_e32 v0, 0x8000, v208
	v_bfe_u32 v1, v6, 3, 1
	v_readfirstlane_b32 s0, v0
	s_mov_b32 m0, s0
	s_mov_b64 s[0:1], 0x42000
	v_add_u32_e32 v0, 0xa000, v208
	v_lshl_add_u64 v[184:185], v[182:183], 0, s[0:1]
	v_readfirstlane_b32 s0, v0
	global_load_lds_dwordx4 v[182:183], off
	s_mov_b32 m0, s0
	s_mov_b64 s[0:1], 0x84000
	v_add_u32_e32 v0, 0xc000, v208
	v_lshl_add_u64 v[186:187], v[182:183], 0, s[0:1]
	v_readfirstlane_b32 s0, v0
	global_load_lds_dwordx4 v[184:185], off
	s_mov_b32 m0, s0
	s_mov_b64 s[0:1], 0xc6000
	v_add_u32_e32 v0, 0xe000, v208
	v_lshl_add_u64 v[188:189], v[182:183], 0, s[0:1]
	v_readfirstlane_b32 s0, v0
	global_load_lds_dwordx4 v[186:187], off
	s_mov_b32 m0, s0
	v_bfe_u32 v0, v6, 2, 1
	global_load_lds_dwordx4 v[188:189], off
	v_mul_u32_u24_e32 v0, 0x440, v0
	v_mul_u32_u24_e32 v1, 0x220, v1
	v_add3_u32 v0, v0, v1, v2
	v_mov_b32_e32 v30, v177
	v_mov_b32_e32 v31, v177
	v_or_b32_e32 v0, v0, v9
	v_mov_b32_e32 v16, v177
	v_mov_b32_e32 v17, v177
	v_mov_b32_e32 v18, v177
	v_mov_b32_e32 v19, v177
	v_mov_b32_e32 v20, v177
	v_mov_b32_e32 v21, v177
	v_mov_b32_e32 v22, v177
	v_mov_b32_e32 v23, v177
	v_mov_b32_e32 v24, v177
	v_mov_b32_e32 v25, v177
	v_mov_b32_e32 v26, v177
	v_mov_b32_e32 v27, v177
	v_mov_b32_e32 v28, v177
	v_mov_b32_e32 v29, v177
	v_mov_b32_e32 v213, 0
	v_mov_b64_e32 v[62:63], v[30:31]
	s_mov_b32 s18, 0
	v_add_u32_e32 v209, 0, v10
	v_xad_u32 v210, v5, 64, 0
	v_xad_u32 v211, v5, 32, 0
	v_add_u32_e32 v212, 0, v0
	v_mov_b32_e32 v32, v177
	v_mov_b32_e32 v33, v177
	v_mov_b32_e32 v34, v177
	v_mov_b32_e32 v35, v177
	v_mov_b32_e32 v36, v177
	v_mov_b32_e32 v37, v177
	v_mov_b32_e32 v38, v177
	v_mov_b32_e32 v39, v177
	v_mov_b32_e32 v40, v177
	v_mov_b32_e32 v41, v177
	v_mov_b32_e32 v42, v177
	v_mov_b32_e32 v43, v177
	v_mov_b32_e32 v44, v177
	v_mov_b32_e32 v45, v177
	v_mov_b32_e32 v46, v177
	v_mov_b32_e32 v47, v177
	v_mov_b32_e32 v0, v177
	v_mov_b32_e32 v1, v177
	v_mov_b32_e32 v2, v177
	v_mov_b32_e32 v3, v177
	v_mov_b32_e32 v4, v177
	v_mov_b32_e32 v5, v177
	v_mov_b32_e32 v6, v177
	v_mov_b32_e32 v7, v177
	v_mov_b32_e32 v8, v177
	v_mov_b32_e32 v9, v177
	v_mov_b32_e32 v10, v177
	v_mov_b32_e32 v11, v177
	v_mov_b32_e32 v12, v177
	v_mov_b32_e32 v13, v177
	v_mov_b32_e32 v14, v177
	v_mov_b32_e32 v15, v177
	s_mov_b64 s[12:13], 0
	v_mov_b32_e32 v214, 0
	v_mov_b32_e32 v220, 0
	v_mov_b32_e32 v219, 0
	v_mov_b64_e32 v[60:61], v[28:29]
	v_mov_b64_e32 v[58:59], v[26:27]
	v_mov_b64_e32 v[56:57], v[24:25]
	v_mov_b64_e32 v[54:55], v[22:23]
	v_mov_b64_e32 v[52:53], v[20:21]
	v_mov_b64_e32 v[50:51], v[18:19]
	v_mov_b64_e32 v[48:49], v[16:17]
	v_mov_b32_e32 v64, 0
	v_mov_b32_e32 v65, v213
	v_mov_b32_e32 v66, v213
	v_mov_b32_e32 v67, v213
	v_mov_b32_e32 v68, v213
	v_mov_b32_e32 v69, v213
	v_mov_b32_e32 v70, v213
	v_mov_b32_e32 v71, v213
	v_mov_b32_e32 v72, v213
	v_mov_b32_e32 v73, v213
	v_mov_b32_e32 v74, v213
	v_mov_b32_e32 v75, v213
	v_mov_b32_e32 v76, v213
	v_mov_b32_e32 v77, v213
	v_mov_b32_e32 v78, v213
	v_mov_b32_e32 v79, v213
	v_mov_b32_e32 v80, 0
	v_mov_b32_e32 v81, v213
	v_mov_b32_e32 v82, v213
	v_mov_b32_e32 v83, v213
	v_mov_b32_e32 v84, v213
	v_mov_b32_e32 v85, v213
	v_mov_b32_e32 v86, v213
	v_mov_b32_e32 v87, v213
	v_mov_b32_e32 v88, v213
	v_mov_b32_e32 v89, v213
	v_mov_b32_e32 v90, v213
	v_mov_b32_e32 v91, v213
	v_mov_b32_e32 v92, v213
	v_mov_b32_e32 v93, v213
	v_mov_b32_e32 v94, v213
	v_mov_b32_e32 v95, v213
	s_waitcnt vmcnt(0)
	.p2alignl 6, 3212836864

.LBB0_580:
	v_pk_add_f32 v[130:131], v[130:131], v[132:133]
	v_pk_add_f32 v[134:135], v[134:135], v[136:137]
	v_pk_add_f32 v[138:139], v[138:139], v[140:141]
	v_add_f32_e32 v129, v129, v160
	v_exp_f32_e32 v96, v96
	v_exp_f32_e32 v97, v97
	v_exp_f32_e32 v98, v98
	v_exp_f32_e32 v99, v99
	v_pk_add_f32 v[130:131], v[130:131], v[134:135]
	v_pk_add_f32 v[138:139], v[138:139], v[142:143]
	v_exp_f32_e32 v100, v100
	v_exp_f32_e32 v101, v101
	v_exp_f32_e32 v102, v102
	v_exp_f32_e32 v103, v103
	v_pk_add_f32 v[130:131], v[130:131], v[138:139]
	v_pk_add_f32 v[132:133], v[96:97], v[98:99]
	v_add_f32_e32 v129, v129, v130
	v_pk_add_f32 v[134:135], v[100:101], v[102:103]
	v_add_f32_e32 v129, v129, v131
	v_cvt_pk_bf16_f32 v96, v96, v97
	v_cvt_pk_bf16_f32 v97, v98, v99
	v_cvt_pk_bf16_f32 v98, v100, v101
	v_cvt_pk_bf16_f32 v99, v102, v103
	v_add_f32_e32 v220, v220, v129
	v_exp_f32_e32 v104, v104
	v_mfma_f32_32x32x16_bf16 v[48:63], v[112:115], v[96:99], v[48:63]
	v_exp_f32_e32 v105, v105
	v_exp_f32_e32 v106, v106
	v_exp_f32_e32 v107, v107
	v_exp_f32_e32 v108, v108
	v_exp_f32_e32 v109, v109
	v_exp_f32_e32 v110, v110
	v_exp_f32_e32 v111, v111
	v_mfma_f32_32x32x16_bf16 v[16:31], v[116:119], v[96:99], v[16:31]
	v_pk_add_f32 v[132:133], v[132:133], v[134:135]
	v_pk_add_f32 v[136:137], v[104:105], v[106:107]
	v_pk_add_f32 v[138:139], v[108:109], v[110:111]
	v_cvt_pk_bf16_f32 v100, v104, v105
	v_cvt_pk_bf16_f32 v101, v106, v107
	v_cvt_pk_bf16_f32 v102, v108, v109
	v_cvt_pk_bf16_f32 v103, v110, v111
	v_pk_add_f32 v[136:137], v[136:137], v[138:139]
	v_pk_add_f32 v[132:133], v[132:133], v[136:137]
	v_mfma_f32_32x32x16_bf16 v[48:63], v[120:123], v[100:103], v[48:63]
	v_add_f32_e32 v129, v132, v133
	s_add_i32 s23, s23, 1
	s_addk_i32 s22, 0x2000
	v_mfma_f32_32x32x16_bf16 v[16:31], v[124:127], v[100:103], v[16:31]
	s_addk_i32 s21, 0x80
	v_add_f32_e32 v219, v128, v129
	s_cmpk_eq_u32 s22, 0x8000
	s_cbranch_scc1 .LBB0_599
	.p2alignl 6, 3212836864

.LBB0_658:
	s_ashr_i32 s2, s0, 7
	s_mul_i32 s1, s2, 33
	s_bfe_u32 s3, s0, 0x50002
	s_add_i32 s10, s1, s3
	s_add_i32 s10, s10, 1
	v_mov_b32_e32 v14, v190
	s_lshl_b32 s17, s10, 8
	s_lshl_b32 s0, s0, 8
	s_and_b32 s12, s0, 0x300
	v_ashrrev_i32_e32 v15, 3, v14
	v_lshrrev_b32_e32 v16, 4, v14
	v_add_u32_e32 v18, s17, v15
	v_xor_b32_e32 v17, v16, v14
	v_add_u32_e32 v2, 64, v18
	v_mov_b64_e32 v[0:1], s[42:43]
	v_add_u32_e32 v4, 0x80, v18
	v_add_u32_e32 v6, 0xc0, v18
	v_add_u32_e32 v12, s12, v15
	v_mov_b64_e32 v[10:11], s[58:59]
	v_mad_i64_i32 v[2:3], s[0:1], v2, s78, v[0:1]
	v_mad_i64_i32 v[4:5], s[0:1], v4, s78, v[0:1]
	v_mad_i64_i32 v[6:7], s[0:1], v6, s78, v[0:1]
	v_mad_i64_i32 v[8:9], s[0:1], v12, s78, 0
	v_mad_i64_i32 v[10:11], s[0:1], v12, s78, v[10:11]
	v_mad_i64_i32 v[12:13], s[0:1], v18, s78, 0
	v_mad_i64_i32 v[0:1], s[0:1], v18, s78, v[0:1]
	v_lshlrev_b32_e32 v17, 4, v17
	v_lshl_add_u32 v150, v14, 4, 0
	v_and_b32_e32 v176, 0x70, v17
	v_readfirstlane_b32 s0, v150
	v_lshl_add_u64 v[0:1], v[0:1], 0, v[176:177]
	s_mov_b32 m0, s0
	v_lshl_add_u64 v[2:3], v[2:3], 0, v[176:177]
	global_load_lds_dwordx4 v[0:1], off
	v_add_u32_e32 v0, 0x2000, v150
	v_lshl_add_u64 v[4:5], v[4:5], 0, v[176:177]
	v_readfirstlane_b32 s0, v0
	v_add_u32_e32 v0, 0x4000, v150
	s_mov_b32 m0, s0
	v_readfirstlane_b32 s0, v0
	v_add_u32_e32 v0, 0x6000, v150
	global_load_lds_dwordx4 v[2:3], off
	s_mov_b32 m0, s0
	v_readfirstlane_b32 s0, v0
	v_add_u32_e32 v0, 0x8000, v150
	v_lshl_add_u64 v[6:7], v[6:7], 0, v[176:177]
	global_load_lds_dwordx4 v[4:5], off
	s_mov_b32 m0, s0
	v_readfirstlane_b32 s0, v0
	v_lshl_add_u64 v[10:11], v[10:11], 0, v[176:177]
	global_load_lds_dwordx4 v[6:7], off
	s_mov_b32 m0, s0
	s_mov_b64 s[0:1], 0x22000
	v_add_u32_e32 v2, 0xa000, v150
	v_lshl_add_u64 v[0:1], v[10:11], 0, s[0:1]
	v_readfirstlane_b32 s0, v2
	global_load_lds_dwordx4 v[10:11], off
	s_mov_b32 m0, s0
	s_mov_b64 s[0:1], 0x44000
	v_add_u32_e32 v2, 0xc000, v150
	global_load_lds_dwordx4 v[0:1], off
	v_lshl_add_u64 v[0:1], v[10:11], 0, s[0:1]
	v_readfirstlane_b32 s0, v2
	s_mov_b32 m0, s0
	s_mov_b64 s[0:1], 0x66000
	v_add_u32_e32 v2, 0xe000, v150
	global_load_lds_dwordx4 v[0:1], off
	v_lshl_add_u64 v[0:1], v[10:11], 0, s[0:1]
	v_readfirstlane_b32 s0, v2
	s_mov_b32 m0, s0
	s_mulk_i32 s2, 0x2100
	global_load_lds_dwordx4 v[0:1], off
	s_lshl_b32 s13, s3, 8
	s_add_i32 s13, s13, s2
	v_bitop3_b32 v0, v16, 7, v14 bitop3:0x48
	v_add_u32_e32 v3, s13, v15
	v_lshlrev_b32_e32 v2, 4, v0
	v_add_u32_e32 v0, 0x140, v3
	v_mad_i64_i32 v[0:1], s[0:1], v0, s78, 0
	v_or_b32_e32 v0, v0, v2
	v_lshl_add_u64 v[130:131], s[48:49], 0, v[0:1]
	v_add_u32_e32 v0, 0x180, v3
	v_mad_i64_i32 v[0:1], s[0:1], v0, s78, 0
	v_and_b32_e32 v139, 15, v14
	v_bfe_u32 v140, v14, 4, 2
	v_bfe_u32 v17, v14, 1, 3
	v_or_b32_e32 v0, v0, v2
	v_lshlrev_b32_e32 v18, 7, v139
	v_bitop3_b32 v19, v16, v17, 3 bitop3:0x6c
	v_bitop3_b32 v17, v140, v17, 4 bitop3:0x36
	v_lshl_add_u64 v[132:133], s[48:49], 0, v[0:1]
	v_add_u32_e32 v0, 0x1c0, v3
	v_lshl_or_b32 v146, v17, 4, v18
	v_ashrrev_i32_e32 v17, 1, v14
	v_mad_i64_i32 v[0:1], s[0:1], v0, s78, 0
	v_bfe_u32 v138, v14, 7, 1
	v_and_b32_e32 v141, 0xffffff80, v17
	v_and_or_b32 v141, v14, 64, v141
	v_or_b32_e32 v12, v12, v2
	v_or_b32_e32 v0, v0, v2
	v_or_b32_e32 v8, v8, v2
	v_mov_b32_e32 v108, 0
	v_lshl_or_b32 v147, v19, 4, v18
	v_lshlrev_b32_e32 v149, 7, v141
	v_lshlrev_b32_e32 v148, 14, v138
	v_lshl_add_u64 v[128:129], s[48:49], 0, v[12:13]
	v_lshl_add_u64 v[134:135], s[48:49], 0, v[0:1]
	v_lshl_add_u64 v[136:137], s[8:9], 0, v[8:9]
	s_mov_b64 s[2:3], 0
	s_mov_b32 s0, 0
	v_mov_b32_e32 v109, v108
	v_mov_b32_e32 v110, v108
	v_mov_b32_e32 v111, v108
	v_mov_b32_e32 v0, v108
	v_mov_b32_e32 v1, v108
	v_mov_b32_e32 v2, v108
	v_mov_b32_e32 v3, v108
	v_mov_b32_e32 v4, v108
	v_mov_b32_e32 v5, v108
	v_mov_b32_e32 v6, v108
	v_mov_b32_e32 v7, v108
	v_mov_b32_e32 v8, v108
	v_mov_b32_e32 v9, v108
	v_mov_b32_e32 v10, v108
	v_mov_b32_e32 v11, v108
	v_mov_b32_e32 v16, v108
	v_mov_b32_e32 v17, v108
	v_mov_b32_e32 v18, v108
	v_mov_b32_e32 v19, v108
	v_mov_b32_e32 v24, v108
	v_mov_b32_e32 v25, v108
	v_mov_b32_e32 v26, v108
	v_mov_b32_e32 v27, v108
	v_mov_b32_e32 v32, v108
	v_mov_b32_e32 v33, v108
	v_mov_b32_e32 v34, v108
	v_mov_b32_e32 v35, v108
	v_mov_b32_e32 v40, v108
	v_mov_b32_e32 v41, v108
	v_mov_b32_e32 v42, v108
	v_mov_b32_e32 v43, v108
	v_mov_b32_e32 v12, v108
	v_mov_b32_e32 v13, v108
	v_mov_b32_e32 v14, v108
	v_mov_b32_e32 v15, v108
	v_mov_b32_e32 v20, v108
	v_mov_b32_e32 v21, v108
	v_mov_b32_e32 v22, v108
	v_mov_b32_e32 v23, v108
	v_mov_b32_e32 v28, v108
	v_mov_b32_e32 v29, v108
	v_mov_b32_e32 v30, v108
	v_mov_b32_e32 v31, v108
	v_mov_b32_e32 v36, v108
	v_mov_b32_e32 v37, v108
	v_mov_b32_e32 v38, v108
	v_mov_b32_e32 v39, v108
	v_mov_b32_e32 v48, v108
	v_mov_b32_e32 v49, v108
	v_mov_b32_e32 v50, v108
	v_mov_b32_e32 v51, v108
	v_mov_b32_e32 v56, v108
	v_mov_b32_e32 v57, v108
	v_mov_b32_e32 v58, v108
	v_mov_b32_e32 v59, v108
	v_mov_b32_e32 v64, v108
	v_mov_b32_e32 v65, v108
	v_mov_b32_e32 v66, v108
	v_mov_b32_e32 v67, v108
	v_mov_b32_e32 v72, v108
	v_mov_b32_e32 v73, v108
	v_mov_b32_e32 v74, v108
	v_mov_b32_e32 v75, v108
	v_mov_b32_e32 v44, v108
	v_mov_b32_e32 v45, v108
	v_mov_b32_e32 v46, v108
	v_mov_b32_e32 v47, v108
	v_mov_b32_e32 v52, v108
	v_mov_b32_e32 v53, v108
	v_mov_b32_e32 v54, v108
	v_mov_b32_e32 v55, v108
	v_mov_b32_e32 v60, v108
	v_mov_b32_e32 v61, v108
	v_mov_b32_e32 v62, v108
	v_mov_b32_e32 v63, v108
	v_mov_b32_e32 v68, v108
	v_mov_b32_e32 v69, v108
	v_mov_b32_e32 v70, v108
	v_mov_b32_e32 v71, v108
	v_mov_b32_e32 v80, v108
	v_mov_b32_e32 v81, v108
	v_mov_b32_e32 v82, v108
	v_mov_b32_e32 v83, v108
	v_mov_b32_e32 v88, v108
	v_mov_b32_e32 v89, v108
	v_mov_b32_e32 v90, v108
	v_mov_b32_e32 v91, v108
	v_mov_b32_e32 v96, v108
	v_mov_b32_e32 v97, v108
	v_mov_b32_e32 v98, v108
	v_mov_b32_e32 v99, v108
	v_mov_b32_e32 v104, v108
	v_mov_b32_e32 v105, v108
	v_mov_b32_e32 v106, v108
	v_mov_b32_e32 v107, v108
	v_mov_b32_e32 v76, v108
	v_mov_b32_e32 v77, v108
	v_mov_b32_e32 v78, v108
	v_mov_b32_e32 v79, v108
	v_mov_b32_e32 v84, v108
	v_mov_b32_e32 v85, v108
	v_mov_b32_e32 v86, v108
	v_mov_b32_e32 v87, v108
	v_mov_b32_e32 v92, v108
	v_mov_b32_e32 v93, v108
	v_mov_b32_e32 v94, v108
	v_mov_b32_e32 v95, v108
	v_mov_b32_e32 v100, v108
	v_mov_b32_e32 v101, v108
	v_mov_b32_e32 v102, v108
	v_mov_b32_e32 v103, v108
	v_mov_b32_e32 v112, v108
	v_mov_b32_e32 v113, v108
	v_mov_b32_e32 v114, v108
	v_mov_b32_e32 v115, v108
	v_mov_b32_e32 v116, v108
	v_mov_b32_e32 v117, v108
	v_mov_b32_e32 v118, v108
	v_mov_b32_e32 v119, v108
	v_mov_b32_e32 v120, v108
	v_mov_b32_e32 v121, v108
	v_mov_b32_e32 v122, v108
	v_mov_b32_e32 v123, v108
	v_mov_b32_e32 v124, v108
	v_mov_b32_e32 v125, v108
	v_mov_b32_e32 v126, v108
	v_mov_b32_e32 v127, v108
	.p2alignl 6, 3212836864

.LBB0_1072:
	s_andn2_b64 vcc, exec, s[2:3]
	s_cbranch_vccnz .LBB0_1067
	v_mov_b32_e32 v20, v190
	s_mulk_i32 s31, 0xfe
	v_mov_b32_e32 v1, v177
	v_ashrrev_i32_e32 v12, 3, v20
	v_add3_u32 v8, s31, -1, v12
	v_med3_i32 v0, v8, 0, v203
	v_mul_u32_u24_e32 v176, 0x880, v0
	v_add_u32_e32 v0, 64, v8
	v_med3_i32 v0, v0, 0, v203
	v_mul_u32_u24_e32 v0, 0x880, v0
	v_lshl_add_u64 v[2:3], s[8:9], 0, v[0:1]
	v_add_u32_e32 v1, 0x80, v8
	v_med3_i32 v1, v1, 0, v203
	v_mul_u32_u24_e32 v4, 0x880, v1
	v_add_u32_e32 v1, 0xc0, v8
	v_lshrrev_b32_e32 v21, 4, v20
	v_med3_i32 v1, v1, 0, v203
	v_xor_b32_e32 v18, v21, v20
	v_mul_u32_u24_e32 v8, 0x880, v1
	v_lshl_add_u32 v1, s30, 8, v12
	v_mov_b64_e32 v[14:15], s[12:13]
	v_mad_i64_i32 v[12:13], s[2:3], v1, s78, 0
	v_mad_i64_i32 v[14:15], s[2:3], v1, s78, v[14:15]
	v_lshlrev_b32_e32 v1, 4, v18
	v_mov_b32_e32 v5, v177
	v_mov_b32_e32 v9, v177
	v_and_b32_e32 v139, 15, v20
	v_and_b32_e32 v18, 0x70, v1
	v_bfe_u32 v140, v20, 4, 2
	v_bfe_u32 v1, v20, 1, 3
	v_lshl_add_u64 v[6:7], s[8:9], 0, v[4:5]
	v_lshl_add_u64 v[10:11], s[8:9], 0, v[8:9]
	v_lshlrev_b32_e32 v5, 7, v139
	v_bitop3_b32 v9, v21, v1, 3 bitop3:0x6c
	v_bitop3_b32 v1, v140, v1, 4 bitop3:0x36
	v_lshl_or_b32 v142, v1, 4, v5
	v_ashrrev_i32_e32 v1, 1, v20
	v_lshl_add_u32 v146, v20, 4, 0
	v_lshl_add_u64 v[16:17], s[8:9], 0, v[176:177]
	v_mov_b32_e32 v19, v177
	v_and_b32_e32 v141, 0xffffff80, v1
	v_and_or_b32 v141, v20, 64, v141
	v_readfirstlane_b32 s2, v146
	v_add_u32_e32 v1, 0x2000, v146
	v_lshl_add_u64 v[16:17], v[16:17], 0, v[18:19]
	s_mov_b32 m0, s2
	v_readfirstlane_b32 s2, v1
	v_add_u32_e32 v1, 0x4000, v146
	v_lshl_add_u64 v[2:3], v[2:3], 0, v[18:19]
	global_load_lds_dwordx4 v[16:17], off
	s_mov_b32 m0, s2
	v_readfirstlane_b32 s2, v1
	v_add_u32_e32 v1, 0x6000, v146
	v_lshl_add_u64 v[6:7], v[6:7], 0, v[18:19]
	global_load_lds_dwordx4 v[2:3], off
	s_mov_b32 m0, s2
	v_readfirstlane_b32 s2, v1
	v_add_u32_e32 v1, 0x8000, v146
	v_lshl_add_u64 v[10:11], v[10:11], 0, v[18:19]
	global_load_lds_dwordx4 v[6:7], off
	s_mov_b32 m0, s2
	v_readfirstlane_b32 s2, v1
	v_lshl_add_u64 v[14:15], v[14:15], 0, v[18:19]
	global_load_lds_dwordx4 v[10:11], off
	s_mov_b32 m0, s2
	s_mov_b64 s[2:3], 0x22000
	v_add_u32_e32 v1, 0xa000, v146
	v_lshl_add_u64 v[2:3], v[14:15], 0, s[2:3]
	v_readfirstlane_b32 s2, v1
	global_load_lds_dwordx4 v[14:15], off
	s_mov_b32 m0, s2
	s_mov_b64 s[2:3], 0x44000
	v_add_u32_e32 v1, 0xc000, v146
	global_load_lds_dwordx4 v[2:3], off
	v_lshl_add_u64 v[2:3], v[14:15], 0, s[2:3]
	v_readfirstlane_b32 s2, v1
	s_mov_b32 m0, s2
	s_mov_b64 s[2:3], 0x66000
	v_add_u32_e32 v1, 0xe000, v146
	global_load_lds_dwordx4 v[2:3], off
	v_lshl_add_u64 v[2:3], v[14:15], 0, s[2:3]
	v_readfirstlane_b32 s2, v1
	s_mov_b32 m0, s2
	v_bitop3_b32 v1, v21, 7, v20 bitop3:0x48
	global_load_lds_dwordx4 v[2:3], off
	v_lshl_or_b32 v143, v9, 4, v5
	v_lshlrev_b32_e32 v5, 4, v1
	v_or_b32_e32 v2, v5, v8
	v_mov_b32_e32 v3, v177
	v_bfe_u32 v138, v20, 7, 1
	v_or_b32_e32 v12, v12, v5
	v_lshl_add_u64 v[130:131], s[28:29], 0, v[2:3]
	v_or_b32_e32 v2, v5, v4
	v_or_b32_e32 v0, v5, v0
	v_mov_b32_e32 v1, v177
	v_or_b32_e32 v176, v5, v176
	v_mov_b32_e32 v108, 0
	s_mov_b32 s4, 0
	v_lshlrev_b32_e32 v144, 7, v141
	v_lshlrev_b32_e32 v145, 14, v138
	v_lshl_add_u64 v[128:129], s[10:11], 0, v[12:13]
	v_lshl_add_u64 v[132:133], s[28:29], 0, v[2:3]
	v_lshl_add_u64 v[134:135], s[28:29], 0, v[0:1]
	v_lshl_add_u64 v[136:137], s[28:29], 0, v[176:177]
	s_mov_b64 s[2:3], 0
	v_mov_b32_e32 v109, v108
	v_mov_b32_e32 v110, v108
	v_mov_b32_e32 v111, v108
	v_mov_b32_e32 v0, v108
	v_mov_b32_e32 v1, v108
	v_mov_b32_e32 v2, v108
	v_mov_b32_e32 v3, v108
	v_mov_b32_e32 v4, v108
	v_mov_b32_e32 v5, v108
	v_mov_b32_e32 v6, v108
	v_mov_b32_e32 v7, v108
	v_mov_b32_e32 v8, v108
	v_mov_b32_e32 v9, v108
	v_mov_b32_e32 v10, v108
	v_mov_b32_e32 v11, v108
	v_mov_b32_e32 v16, v108
	v_mov_b32_e32 v17, v108
	v_mov_b32_e32 v18, v108
	v_mov_b32_e32 v19, v108
	v_mov_b32_e32 v24, v108
	v_mov_b32_e32 v25, v108
	v_mov_b32_e32 v26, v108
	v_mov_b32_e32 v27, v108
	v_mov_b32_e32 v32, v108
	v_mov_b32_e32 v33, v108
	v_mov_b32_e32 v34, v108
	v_mov_b32_e32 v35, v108
	v_mov_b32_e32 v40, v108
	v_mov_b32_e32 v41, v108
	v_mov_b32_e32 v42, v108
	v_mov_b32_e32 v43, v108
	v_mov_b32_e32 v12, v108
	v_mov_b32_e32 v13, v108
	v_mov_b32_e32 v14, v108
	v_mov_b32_e32 v15, v108
	v_mov_b32_e32 v20, v108
	v_mov_b32_e32 v21, v108
	v_mov_b32_e32 v22, v108
	v_mov_b32_e32 v23, v108
	v_mov_b32_e32 v28, v108
	v_mov_b32_e32 v29, v108
	v_mov_b32_e32 v30, v108
	v_mov_b32_e32 v31, v108
	v_mov_b32_e32 v36, v108
	v_mov_b32_e32 v37, v108
	v_mov_b32_e32 v38, v108
	v_mov_b32_e32 v39, v108
	v_mov_b32_e32 v48, v108
	v_mov_b32_e32 v49, v108
	v_mov_b32_e32 v50, v108
	v_mov_b32_e32 v51, v108
	v_mov_b32_e32 v56, v108
	v_mov_b32_e32 v57, v108
	v_mov_b32_e32 v58, v108
	v_mov_b32_e32 v59, v108
	v_mov_b32_e32 v64, v108
	v_mov_b32_e32 v65, v108
	v_mov_b32_e32 v66, v108
	v_mov_b32_e32 v67, v108
	v_mov_b32_e32 v72, v108
	v_mov_b32_e32 v73, v108
	v_mov_b32_e32 v74, v108
	v_mov_b32_e32 v75, v108
	v_mov_b32_e32 v44, v108
	v_mov_b32_e32 v45, v108
	v_mov_b32_e32 v46, v108
	v_mov_b32_e32 v47, v108
	v_mov_b32_e32 v52, v108
	v_mov_b32_e32 v53, v108
	v_mov_b32_e32 v54, v108
	v_mov_b32_e32 v55, v108
	v_mov_b32_e32 v60, v108
	v_mov_b32_e32 v61, v108
	v_mov_b32_e32 v62, v108
	v_mov_b32_e32 v63, v108
	v_mov_b32_e32 v68, v108
	v_mov_b32_e32 v69, v108
	v_mov_b32_e32 v70, v108
	v_mov_b32_e32 v71, v108
	v_mov_b32_e32 v80, v108
	v_mov_b32_e32 v81, v108
	v_mov_b32_e32 v82, v108
	v_mov_b32_e32 v83, v108
	v_mov_b32_e32 v88, v108
	v_mov_b32_e32 v89, v108
	v_mov_b32_e32 v90, v108
	v_mov_b32_e32 v91, v108
	v_mov_b32_e32 v96, v108
	v_mov_b32_e32 v97, v108
	v_mov_b32_e32 v98, v108
	v_mov_b32_e32 v99, v108
	v_mov_b32_e32 v104, v108
	v_mov_b32_e32 v105, v108
	v_mov_b32_e32 v106, v108
	v_mov_b32_e32 v107, v108
	v_mov_b32_e32 v76, v108
	v_mov_b32_e32 v77, v108
	v_mov_b32_e32 v78, v108
	v_mov_b32_e32 v79, v108
	v_mov_b32_e32 v84, v108
	v_mov_b32_e32 v85, v108
	v_mov_b32_e32 v86, v108
	v_mov_b32_e32 v87, v108
	v_mov_b32_e32 v92, v108
	v_mov_b32_e32 v93, v108
	v_mov_b32_e32 v94, v108
	v_mov_b32_e32 v95, v108
	v_mov_b32_e32 v100, v108
	v_mov_b32_e32 v101, v108
	v_mov_b32_e32 v102, v108
	v_mov_b32_e32 v103, v108
	v_mov_b32_e32 v112, v108
	v_mov_b32_e32 v113, v108
	v_mov_b32_e32 v114, v108
	v_mov_b32_e32 v115, v108
	v_mov_b32_e32 v116, v108
	v_mov_b32_e32 v117, v108
	v_mov_b32_e32 v118, v108
	v_mov_b32_e32 v119, v108
	v_mov_b32_e32 v120, v108
	v_mov_b32_e32 v121, v108
	v_mov_b32_e32 v122, v108
	v_mov_b32_e32 v123, v108
	v_mov_b32_e32 v124, v108
	v_mov_b32_e32 v125, v108
	v_mov_b32_e32 v126, v108
	v_mov_b32_e32 v127, v108
	.p2alignl 6, 3212836864

.LBB0_1142:
	s_ashr_i32 s10, s2, 7
	s_mul_i32 s3, s10, 33
	s_bfe_u32 s11, s2, 0x50002
	s_add_i32 s13, s3, s11
	s_add_i32 s13, s13, 1
	v_mov_b32_e32 v14, v190
	s_lshl_b32 s17, s13, 8
	s_lshl_b32 s2, s2, 8
	s_and_b32 s12, s2, 0x300
	v_ashrrev_i32_e32 v15, 3, v14
	v_lshrrev_b32_e32 v16, 4, v14
	v_add_u32_e32 v18, s17, v15
	v_xor_b32_e32 v17, v16, v14
	v_add_u32_e32 v2, 64, v18
	v_mov_b64_e32 v[0:1], s[46:47]
	v_add_u32_e32 v4, 0x80, v18
	v_add_u32_e32 v6, 0xc0, v18
	v_add_u32_e32 v12, s12, v15
	v_mov_b64_e32 v[10:11], s[40:41]
	v_mad_i64_i32 v[2:3], s[2:3], v2, s87, v[0:1]
	v_mad_i64_i32 v[4:5], s[2:3], v4, s87, v[0:1]
	v_mad_i64_i32 v[6:7], s[2:3], v6, s87, v[0:1]
	v_mad_i64_i32 v[8:9], s[2:3], v12, s87, 0
	v_mad_i64_i32 v[10:11], s[2:3], v12, s87, v[10:11]
	v_mad_i64_i32 v[12:13], s[2:3], v18, s87, 0
	v_mad_i64_i32 v[0:1], s[2:3], v18, s87, v[0:1]
	v_lshlrev_b32_e32 v17, 4, v17
	v_lshl_add_u32 v150, v14, 4, 0
	v_and_b32_e32 v176, 0x70, v17
	v_readfirstlane_b32 s2, v150
	v_lshl_add_u64 v[0:1], v[0:1], 0, v[176:177]
	s_mov_b32 m0, s2
	v_lshl_add_u64 v[2:3], v[2:3], 0, v[176:177]
	global_load_lds_dwordx4 v[0:1], off
	v_add_u32_e32 v0, 0x2000, v150
	v_lshl_add_u64 v[4:5], v[4:5], 0, v[176:177]
	v_readfirstlane_b32 s2, v0
	v_add_u32_e32 v0, 0x4000, v150
	s_mov_b32 m0, s2
	v_readfirstlane_b32 s2, v0
	v_add_u32_e32 v0, 0x6000, v150
	global_load_lds_dwordx4 v[2:3], off
	s_mov_b32 m0, s2
	v_readfirstlane_b32 s2, v0
	v_add_u32_e32 v0, 0x8000, v150
	v_lshl_add_u64 v[6:7], v[6:7], 0, v[176:177]
	global_load_lds_dwordx4 v[4:5], off
	s_mov_b32 m0, s2
	v_readfirstlane_b32 s2, v0
	v_lshl_add_u64 v[10:11], v[10:11], 0, v[176:177]
	global_load_lds_dwordx4 v[6:7], off
	s_mov_b32 m0, s2
	s_mov_b64 s[2:3], 0x58000
	v_add_u32_e32 v2, 0xa000, v150
	v_lshl_add_u64 v[0:1], v[10:11], 0, s[2:3]
	v_readfirstlane_b32 s2, v2
	global_load_lds_dwordx4 v[10:11], off
	s_mov_b32 m0, s2
	s_mov_b64 s[2:3], 0xb0000
	v_add_u32_e32 v2, 0xc000, v150
	global_load_lds_dwordx4 v[0:1], off
	v_lshl_add_u64 v[0:1], v[10:11], 0, s[2:3]
	v_readfirstlane_b32 s2, v2
	s_mov_b32 m0, s2
	s_mov_b64 s[2:3], 0x108000
	v_add_u32_e32 v2, 0xe000, v150
	global_load_lds_dwordx4 v[0:1], off
	v_lshl_add_u64 v[0:1], v[10:11], 0, s[2:3]
	v_readfirstlane_b32 s2, v2
	s_mov_b32 m0, s2
	s_mulk_i32 s10, 0x2100
	global_load_lds_dwordx4 v[0:1], off
	s_lshl_b32 s18, s11, 8
	s_add_i32 s18, s18, s10
	v_bitop3_b32 v0, v16, 7, v14 bitop3:0x48
	v_add_u32_e32 v3, s18, v15
	v_lshlrev_b32_e32 v2, 4, v0
	v_add_u32_e32 v0, 0x140, v3
	v_mad_i64_i32 v[0:1], s[2:3], v0, s87, 0
	v_or_b32_e32 v0, v0, v2
	v_lshl_add_u64 v[130:131], s[50:51], 0, v[0:1]
	v_add_u32_e32 v0, 0x180, v3
	v_mad_i64_i32 v[0:1], s[2:3], v0, s87, 0
	v_and_b32_e32 v139, 15, v14
	v_bfe_u32 v140, v14, 4, 2
	v_bfe_u32 v17, v14, 1, 3
	v_or_b32_e32 v0, v0, v2
	v_lshlrev_b32_e32 v18, 7, v139
	v_bitop3_b32 v19, v16, v17, 3 bitop3:0x6c
	v_bitop3_b32 v17, v140, v17, 4 bitop3:0x36
	v_lshl_add_u64 v[132:133], s[50:51], 0, v[0:1]
	v_add_u32_e32 v0, 0x1c0, v3
	v_lshl_or_b32 v146, v17, 4, v18
	v_ashrrev_i32_e32 v17, 1, v14
	v_mad_i64_i32 v[0:1], s[2:3], v0, s87, 0
	v_bfe_u32 v138, v14, 7, 1
	v_and_b32_e32 v141, 0xffffff80, v17
	v_and_or_b32 v141, v14, 64, v141
	v_or_b32_e32 v12, v12, v2
	v_or_b32_e32 v0, v0, v2
	v_or_b32_e32 v8, v8, v2
	v_mov_b32_e32 v108, 0
	v_lshl_or_b32 v147, v19, 4, v18
	v_lshlrev_b32_e32 v149, 7, v141
	v_lshlrev_b32_e32 v148, 14, v138
	v_lshl_add_u64 v[128:129], s[50:51], 0, v[12:13]
	v_lshl_add_u64 v[134:135], s[50:51], 0, v[0:1]
	v_lshl_add_u64 v[136:137], s[8:9], 0, v[8:9]
	s_mov_b64 s[2:3], 0
	s_mov_b32 s10, 0
	v_mov_b32_e32 v109, v108
	v_mov_b32_e32 v110, v108
	v_mov_b32_e32 v111, v108
	v_mov_b32_e32 v0, v108
	v_mov_b32_e32 v1, v108
	v_mov_b32_e32 v2, v108
	v_mov_b32_e32 v3, v108
	v_mov_b32_e32 v4, v108
	v_mov_b32_e32 v5, v108
	v_mov_b32_e32 v6, v108
	v_mov_b32_e32 v7, v108
	v_mov_b32_e32 v8, v108
	v_mov_b32_e32 v9, v108
	v_mov_b32_e32 v10, v108
	v_mov_b32_e32 v11, v108
	v_mov_b32_e32 v16, v108
	v_mov_b32_e32 v17, v108
	v_mov_b32_e32 v18, v108
	v_mov_b32_e32 v19, v108
	v_mov_b32_e32 v24, v108
	v_mov_b32_e32 v25, v108
	v_mov_b32_e32 v26, v108
	v_mov_b32_e32 v27, v108
	v_mov_b32_e32 v32, v108
	v_mov_b32_e32 v33, v108
	v_mov_b32_e32 v34, v108
	v_mov_b32_e32 v35, v108
	v_mov_b32_e32 v40, v108
	v_mov_b32_e32 v41, v108
	v_mov_b32_e32 v42, v108
	v_mov_b32_e32 v43, v108
	v_mov_b32_e32 v12, v108
	v_mov_b32_e32 v13, v108
	v_mov_b32_e32 v14, v108
	v_mov_b32_e32 v15, v108
	v_mov_b32_e32 v20, v108
	v_mov_b32_e32 v21, v108
	v_mov_b32_e32 v22, v108
	v_mov_b32_e32 v23, v108
	v_mov_b32_e32 v28, v108
	v_mov_b32_e32 v29, v108
	v_mov_b32_e32 v30, v108
	v_mov_b32_e32 v31, v108
	v_mov_b32_e32 v36, v108
	v_mov_b32_e32 v37, v108
	v_mov_b32_e32 v38, v108
	v_mov_b32_e32 v39, v108
	v_mov_b32_e32 v48, v108
	v_mov_b32_e32 v49, v108
	v_mov_b32_e32 v50, v108
	v_mov_b32_e32 v51, v108
	v_mov_b32_e32 v56, v108
	v_mov_b32_e32 v57, v108
	v_mov_b32_e32 v58, v108
	v_mov_b32_e32 v59, v108
	v_mov_b32_e32 v64, v108
	v_mov_b32_e32 v65, v108
	v_mov_b32_e32 v66, v108
	v_mov_b32_e32 v67, v108
	v_mov_b32_e32 v72, v108
	v_mov_b32_e32 v73, v108
	v_mov_b32_e32 v74, v108
	v_mov_b32_e32 v75, v108
	v_mov_b32_e32 v44, v108
	v_mov_b32_e32 v45, v108
	v_mov_b32_e32 v46, v108
	v_mov_b32_e32 v47, v108
	v_mov_b32_e32 v52, v108
	v_mov_b32_e32 v53, v108
	v_mov_b32_e32 v54, v108
	v_mov_b32_e32 v55, v108
	v_mov_b32_e32 v60, v108
	v_mov_b32_e32 v61, v108
	v_mov_b32_e32 v62, v108
	v_mov_b32_e32 v63, v108
	v_mov_b32_e32 v68, v108
	v_mov_b32_e32 v69, v108
	v_mov_b32_e32 v70, v108
	v_mov_b32_e32 v71, v108
	v_mov_b32_e32 v80, v108
	v_mov_b32_e32 v81, v108
	v_mov_b32_e32 v82, v108
	v_mov_b32_e32 v83, v108
	v_mov_b32_e32 v88, v108
	v_mov_b32_e32 v89, v108
	v_mov_b32_e32 v90, v108
	v_mov_b32_e32 v91, v108
	v_mov_b32_e32 v96, v108
	v_mov_b32_e32 v97, v108
	v_mov_b32_e32 v98, v108
	v_mov_b32_e32 v99, v108
	v_mov_b32_e32 v104, v108
	v_mov_b32_e32 v105, v108
	v_mov_b32_e32 v106, v108
	v_mov_b32_e32 v107, v108
	v_mov_b32_e32 v76, v108
	v_mov_b32_e32 v77, v108
	v_mov_b32_e32 v78, v108
	v_mov_b32_e32 v79, v108
	v_mov_b32_e32 v84, v108
	v_mov_b32_e32 v85, v108
	v_mov_b32_e32 v86, v108
	v_mov_b32_e32 v87, v108
	v_mov_b32_e32 v92, v108
	v_mov_b32_e32 v93, v108
	v_mov_b32_e32 v94, v108
	v_mov_b32_e32 v95, v108
	v_mov_b32_e32 v100, v108
	v_mov_b32_e32 v101, v108
	v_mov_b32_e32 v102, v108
	v_mov_b32_e32 v103, v108
	v_mov_b32_e32 v112, v108
	v_mov_b32_e32 v113, v108
	v_mov_b32_e32 v114, v108
	v_mov_b32_e32 v115, v108
	v_mov_b32_e32 v116, v108
	v_mov_b32_e32 v117, v108
	v_mov_b32_e32 v118, v108
	v_mov_b32_e32 v119, v108
	v_mov_b32_e32 v120, v108
	v_mov_b32_e32 v121, v108
	v_mov_b32_e32 v122, v108
	v_mov_b32_e32 v123, v108
	v_mov_b32_e32 v124, v108
	v_mov_b32_e32 v125, v108
	v_mov_b32_e32 v126, v108
	v_mov_b32_e32 v127, v108
	.p2alignl 6, 3212836864
